# DF epilogue: exchange reads pipelined through free VGPR ring, 16 sub-norm swizzle reductions batched
# speedup vs baseline: 1.0067x; 1.0067x over previous
; template <bool FIXED>
; __device__ __forceinline__ void df_unit(LAS char* lds, bf16_t* QKV, const float* gsub, float lam, float post, int b, int h, int qb, int wave0, float mfix2) {
;     ...
; #pragma unroll
;         for (int d = 0; d < 8; ++d)
; #pragma unroll
;             for (int r = 0; r < 16; ++r) { const float v = o[d][r] * rli[r] - xch[(d * 16 + r) * 64]; o[d][r] = v; ssq[r] += v * v; }
.LBB0_154:
	s_cmpk_gt_u32 s16, 0xff
	s_waitcnt lgkmcnt(0)
	s_barrier
	s_cbranch_scc1 .LBB0_156
	ds_read2st64_b32 v[180:181], v174 offset1:1
	ds_read2st64_b32 v[182:183], v174 offset0:10 offset1:11
	ds_read2st64_b32 v[184:185], v174 offset0:2 offset1:3
	ds_read2st64_b32 v[186:187], v174 offset0:4 offset1:5
	ds_read2st64_b32 v[188:189], v174 offset0:6 offset1:7
	ds_read2st64_b32 v[190:191], v174 offset0:8 offset1:9
	ds_read2st64_b32 v[192:193], v174 offset0:12 offset1:13
	ds_read2st64_b32 v[194:195], v174 offset0:14 offset1:15
	ds_read2st64_b32 v[196:197], v174 offset0:16 offset1:17
	ds_read2st64_b32 v[198:199], v174 offset0:18 offset1:19
	ds_read2st64_b32 v[200:201], v174 offset0:20 offset1:21
	ds_read2st64_b32 v[206:207], v174 offset0:22 offset1:23
	ds_read2st64_b32 v[208:209], v174 offset0:24 offset1:25
	ds_read2st64_b32 v[210:211], v174 offset0:26 offset1:27
	s_movk_i32 s0, 0x6000
	s_waitcnt lgkmcnt(13)
	v_fma_f32 v135, v114, v0, -v180
	v_fma_f32 v131, v115, v136, -v181
	ds_read2st64_b32 v[212:213], v174 offset0:28 offset1:29
	s_waitcnt lgkmcnt(12)
	v_fma_f32 v132, v116, v137, -v184
	v_fma_f32 v117, v117, v138, -v185
	ds_read2st64_b32 v[214:215], v174 offset0:30 offset1:31
	s_waitcnt lgkmcnt(12)
	v_fma_f32 v130, v118, v139, -v186
	v_fma_f32 v115, v119, v141, -v187
	ds_read2st64_b32 v[218:219], v174 offset0:32 offset1:33
	s_waitcnt lgkmcnt(12)
	v_fma_f32 v134, v120, v140, -v188
	v_fma_f32 v119, v121, v142, -v189
	ds_read2st64_b32 v[220:221], v174 offset0:34 offset1:35
	v_fma_f32 v118, v125, v145, -v183
	s_waitcnt lgkmcnt(12)
	v_fma_f32 v133, v122, v144, -v190
	v_fma_f32 v120, v123, v146, -v191
	v_fma_f32 v123, v124, v143, -v182
	ds_read2st64_b32 v[226:227], v174 offset0:36 offset1:37
	s_waitcnt lgkmcnt(12)
	v_fma_f32 v122, v126, v167, -v192
	v_fma_f32 v116, v127, v169, -v193
	ds_read2st64_b32 v[228:229], v174 offset0:38 offset1:39
	ds_read2st64_b32 v[234:235], v174 offset0:40 offset1:41
	s_waitcnt lgkmcnt(13)
	v_fma_f32 v121, v129, v173, -v195
	s_waitcnt lgkmcnt(12)
	v_fma_f32 v114, v98, v0, -v196
	v_fma_f32 v98, v99, v136, -v197
	ds_read2st64_b32 v[236:237], v174 offset0:42 offset1:43
	v_fma_f32 v124, v128, v170, -v194
	v_mul_f32_e32 v179, v114, v114
	v_fmac_f32_e32 v179, v135, v135
	v_mul_f32_e32 v178, v98, v98
	s_waitcnt lgkmcnt(12)
	v_fma_f32 v100, v100, v137, -v198
	v_fma_f32 v99, v101, v138, -v199
	ds_read2st64_b32 v[238:239], v174 offset0:44 offset1:45
	v_fmac_f32_e32 v178, v131, v131
	v_mul_f32_e32 v177, v100, v100
	v_fmac_f32_e32 v177, v132, v132
	v_mul_f32_e32 v176, v99, v99
	s_waitcnt lgkmcnt(12)
	v_fma_f32 v102, v102, v139, -v200
	v_fma_f32 v101, v103, v141, -v201
	ds_read2st64_b32 v[240:241], v174 offset0:46 offset1:47
	v_fmac_f32_e32 v176, v117, v117
	v_mul_f32_e32 v175, v102, v102
	v_fmac_f32_e32 v175, v130, v130
	v_mul_f32_e32 v171, v101, v101
	s_waitcnt lgkmcnt(12)
	v_fma_f32 v104, v104, v140, -v206
	v_fma_f32 v103, v105, v142, -v207
	ds_read2st64_b32 v[242:243], v174 offset0:48 offset1:49
	v_fmac_f32_e32 v171, v115, v115
	v_mul_f32_e32 v172, v104, v104
	v_fmac_f32_e32 v172, v134, v134
	v_mul_f32_e32 v168, v103, v103
	s_waitcnt lgkmcnt(12)
	v_fma_f32 v106, v106, v144, -v208
	v_fma_f32 v105, v107, v146, -v209
	ds_read2st64_b32 v[244:245], v174 offset0:50 offset1:51
	v_fmac_f32_e32 v168, v119, v119
	v_mul_f32_e32 v166, v106, v106
	v_fmac_f32_e32 v166, v133, v133
	v_mul_f32_e32 v161, v105, v105
	s_waitcnt lgkmcnt(12)
	v_fma_f32 v108, v108, v143, -v210
	v_fma_f32 v107, v109, v145, -v211
	ds_read2st64_b32 v[246:247], v174 offset0:52 offset1:53
	v_fmac_f32_e32 v161, v120, v120
	v_mul_f32_e32 v154, v108, v108
	v_fmac_f32_e32 v154, v123, v123
	v_mul_f32_e32 v147, v107, v107
	s_waitcnt lgkmcnt(12)
	v_fma_f32 v110, v110, v167, -v212
	v_fma_f32 v109, v111, v169, -v213
	ds_read2st64_b32 v[248:249], v174 offset0:54 offset1:55
	v_fmac_f32_e32 v147, v118, v118
	v_mul_f32_e32 v149, v110, v110
	v_fmac_f32_e32 v149, v122, v122
	v_mul_f32_e32 v148, v109, v109
	s_waitcnt lgkmcnt(12)
	v_fma_f32 v112, v112, v170, -v214
	v_fma_f32 v113, v113, v173, -v215
	ds_read2st64_b32 v[180:181], v174 offset0:56 offset1:57
	v_fmac_f32_e32 v148, v116, v116
	v_mul_f32_e32 v158, v112, v112
	v_fmac_f32_e32 v158, v124, v124
	v_mul_f32_e32 v156, v113, v113
	s_waitcnt lgkmcnt(12)
	v_fma_f32 v111, v82, v0, -v218
	v_fma_f32 v82, v83, v136, -v219
	ds_read2st64_b32 v[184:185], v174 offset0:58 offset1:59
	v_fmac_f32_e32 v179, v111, v111
	v_fmac_f32_e32 v178, v82, v82
	v_fmac_f32_e32 v156, v121, v121
	s_waitcnt lgkmcnt(12)
	v_fma_f32 v84, v84, v137, -v220
	v_fma_f32 v83, v85, v138, -v221
	ds_read2st64_b32 v[186:187], v174 offset0:60 offset1:61
	v_fmac_f32_e32 v177, v84, v84
	v_fmac_f32_e32 v176, v83, v83
	s_waitcnt lgkmcnt(12)
	v_fma_f32 v86, v86, v139, -v226
	v_fma_f32 v85, v87, v141, -v227
	ds_read2st64_b32 v[188:189], v174 offset0:62 offset1:63
	v_fmac_f32_e32 v175, v86, v86
	v_fmac_f32_e32 v171, v85, v85
	s_waitcnt lgkmcnt(12)
	v_fma_f32 v88, v88, v140, -v228
	v_fma_f32 v87, v89, v142, -v229
	ds_read2st64_b32 v[190:191], v174 offset0:64 offset1:65
	v_fmac_f32_e32 v172, v88, v88
	v_fmac_f32_e32 v168, v87, v87
	s_waitcnt lgkmcnt(12)
	v_fma_f32 v90, v90, v144, -v234
	v_fma_f32 v89, v91, v146, -v235
	ds_read2st64_b32 v[182:183], v174 offset0:66 offset1:67
	v_fmac_f32_e32 v166, v90, v90
	v_fmac_f32_e32 v161, v89, v89
	s_waitcnt lgkmcnt(12)
	v_fma_f32 v92, v92, v143, -v236
	v_fma_f32 v91, v93, v145, -v237
	ds_read2st64_b32 v[192:193], v174 offset0:68 offset1:69
	v_fmac_f32_e32 v154, v92, v92
	v_fmac_f32_e32 v147, v91, v91
	s_waitcnt lgkmcnt(12)
	v_fma_f32 v94, v94, v167, -v238
	v_fma_f32 v93, v95, v169, -v239
	ds_read2st64_b32 v[196:197], v174 offset0:70 offset1:71
	v_fmac_f32_e32 v149, v94, v94
	v_fmac_f32_e32 v148, v93, v93
	s_waitcnt lgkmcnt(12)
; template <bool FIXED>
; __device__ __forceinline__ void df_unit(LAS char* lds, bf16_t* QKV, const float* gsub, float lam, float post, int b, int h, int qb, int wave0, float mfix2) {
;     ...
;         for (int d = 0; d < 8; ++d)
; #pragma unroll
;             for (int r = 0; r < 16; ++r) { const float v = o[d][r] * rli[r] - xch[(d * 16 + r) * 64]; o[d][r] = v; ssq[r] += v * v; }
	v_fma_f32 v125, v96, v170, -v240
	v_fma_f32 v96, v97, v173, -v241
	ds_read2st64_b32 v[194:195], v174 offset0:72 offset1:73
	v_fmac_f32_e32 v158, v125, v125
	v_fmac_f32_e32 v156, v96, v96
	s_waitcnt lgkmcnt(12)
	v_fma_f32 v95, v66, v0, -v242
	v_fma_f32 v66, v67, v136, -v243
	ds_read2st64_b32 v[198:199], v174 offset0:74 offset1:75
	v_fmac_f32_e32 v179, v95, v95
	v_fmac_f32_e32 v178, v66, v66
	s_waitcnt lgkmcnt(12)
	v_fma_f32 v68, v68, v137, -v244
	v_fma_f32 v67, v69, v138, -v245
	ds_read2st64_b32 v[200:201], v174 offset0:76 offset1:77
	v_fmac_f32_e32 v177, v68, v68
	v_fmac_f32_e32 v176, v67, v67
	s_waitcnt lgkmcnt(12)
	v_fma_f32 v70, v70, v139, -v246
	v_fma_f32 v69, v71, v141, -v247
	ds_read2st64_b32 v[206:207], v174 offset0:78 offset1:79
	v_fmac_f32_e32 v175, v70, v70
	v_fmac_f32_e32 v171, v69, v69
	s_waitcnt lgkmcnt(12)
	v_fma_f32 v72, v72, v140, -v248
	v_fma_f32 v71, v73, v142, -v249
	ds_read2st64_b32 v[208:209], v174 offset0:80 offset1:81
	v_fmac_f32_e32 v172, v72, v72
	v_fmac_f32_e32 v168, v71, v71
	s_waitcnt lgkmcnt(12)
	v_fma_f32 v74, v74, v144, -v180
	v_fma_f32 v73, v75, v146, -v181
	ds_read2st64_b32 v[210:211], v174 offset0:82 offset1:83
	v_fmac_f32_e32 v166, v74, v74
	v_fmac_f32_e32 v161, v73, v73
	s_waitcnt lgkmcnt(12)
	v_fma_f32 v76, v76, v143, -v184
	v_fma_f32 v75, v77, v145, -v185
	ds_read2st64_b32 v[212:213], v174 offset0:84 offset1:85
	v_fmac_f32_e32 v154, v76, v76
	v_fmac_f32_e32 v147, v75, v75
	s_waitcnt lgkmcnt(12)
	v_fma_f32 v78, v78, v167, -v186
	v_fma_f32 v77, v79, v169, -v187
	ds_read2st64_b32 v[214:215], v174 offset0:86 offset1:87
	v_fmac_f32_e32 v149, v78, v78
	v_fmac_f32_e32 v148, v77, v77
	s_waitcnt lgkmcnt(12)
	v_fma_f32 v97, v80, v170, -v188
	v_fma_f32 v80, v81, v173, -v189
	ds_read2st64_b32 v[218:219], v174 offset0:88 offset1:89
	v_fmac_f32_e32 v158, v97, v97
	v_fmac_f32_e32 v156, v80, v80
	s_waitcnt lgkmcnt(12)
	v_fma_f32 v79, v50, v0, -v190
	v_fma_f32 v50, v51, v136, -v191
	ds_read2st64_b32 v[220:221], v174 offset0:90 offset1:91
	v_fmac_f32_e32 v179, v79, v79
	v_fmac_f32_e32 v178, v50, v50
	s_waitcnt lgkmcnt(12)
	v_fma_f32 v52, v52, v137, -v182
	v_fma_f32 v51, v53, v138, -v183
	ds_read2st64_b32 v[226:227], v174 offset0:92 offset1:93
	v_fmac_f32_e32 v177, v52, v52
	v_fmac_f32_e32 v176, v51, v51
	s_waitcnt lgkmcnt(12)
	v_fma_f32 v54, v54, v139, -v192
	v_fma_f32 v53, v55, v141, -v193
	ds_read2st64_b32 v[228:229], v174 offset0:94 offset1:95
	v_fmac_f32_e32 v175, v54, v54
	v_fmac_f32_e32 v171, v53, v53
	s_waitcnt lgkmcnt(12)
	v_fma_f32 v56, v56, v140, -v196
	v_fma_f32 v55, v57, v142, -v197
	ds_read2st64_b32 v[234:235], v174 offset0:96 offset1:97
	v_fmac_f32_e32 v172, v56, v56
	v_fmac_f32_e32 v168, v55, v55
	s_waitcnt lgkmcnt(12)
	v_fma_f32 v58, v58, v144, -v194
	v_fma_f32 v57, v59, v146, -v195
	ds_read2st64_b32 v[236:237], v174 offset0:98 offset1:99
	v_fmac_f32_e32 v166, v58, v58
	v_fmac_f32_e32 v161, v57, v57
	s_waitcnt lgkmcnt(12)
	v_fma_f32 v60, v60, v143, -v198
	v_fma_f32 v59, v61, v145, -v199
	ds_read2st64_b32 v[238:239], v174 offset0:100 offset1:101
	v_fmac_f32_e32 v154, v60, v60
	v_fmac_f32_e32 v147, v59, v59
	s_waitcnt lgkmcnt(12)
	v_fma_f32 v62, v62, v167, -v200
	v_fma_f32 v61, v63, v169, -v201
	ds_read2st64_b32 v[240:241], v174 offset0:102 offset1:103
	v_fmac_f32_e32 v149, v62, v62
	v_fmac_f32_e32 v148, v61, v61
	s_waitcnt lgkmcnt(12)
	v_fma_f32 v81, v64, v170, -v206
	v_fma_f32 v64, v65, v173, -v207
	ds_read2st64_b32 v[242:243], v174 offset0:104 offset1:105
	v_fmac_f32_e32 v158, v81, v81
	v_fmac_f32_e32 v156, v64, v64
	s_waitcnt lgkmcnt(12)
	v_fma_f32 v63, v34, v0, -v208
	v_fma_f32 v34, v35, v136, -v209
	ds_read2st64_b32 v[244:245], v174 offset0:106 offset1:107
	v_fmac_f32_e32 v179, v63, v63
	v_fmac_f32_e32 v178, v34, v34
	s_waitcnt lgkmcnt(12)
	v_fma_f32 v36, v36, v137, -v210
	v_fma_f32 v35, v37, v138, -v211
	ds_read2st64_b32 v[246:247], v174 offset0:108 offset1:109
	v_fmac_f32_e32 v177, v36, v36
	v_fmac_f32_e32 v176, v35, v35
	s_waitcnt lgkmcnt(12)
	v_fma_f32 v38, v38, v139, -v212
	v_fma_f32 v37, v39, v141, -v213
	ds_read2st64_b32 v[248:249], v174 offset0:110 offset1:111
	v_fmac_f32_e32 v175, v38, v38
	v_fmac_f32_e32 v171, v37, v37
	s_waitcnt lgkmcnt(12)
	v_fma_f32 v40, v40, v140, -v214
	v_fma_f32 v39, v41, v142, -v215
	ds_read2st64_b32 v[180:181], v174 offset0:112 offset1:113
	v_fmac_f32_e32 v172, v40, v40
	v_fmac_f32_e32 v168, v39, v39
	s_waitcnt lgkmcnt(12)
	v_fma_f32 v42, v42, v144, -v218
	v_fma_f32 v41, v43, v146, -v219
	ds_read2st64_b32 v[184:185], v174 offset0:114 offset1:115
	v_fmac_f32_e32 v166, v42, v42
	v_fmac_f32_e32 v161, v41, v41
	s_waitcnt lgkmcnt(12)
	v_fma_f32 v44, v44, v143, -v220
	v_fma_f32 v43, v45, v145, -v221
	ds_read2st64_b32 v[186:187], v174 offset0:116 offset1:117
	v_fmac_f32_e32 v154, v44, v44
	v_fmac_f32_e32 v147, v43, v43
	s_waitcnt lgkmcnt(12)
	v_fma_f32 v46, v46, v167, -v226
	v_fma_f32 v45, v47, v169, -v227
	ds_read2st64_b32 v[188:189], v174 offset0:118 offset1:119
	v_fmac_f32_e32 v149, v46, v46
	v_fmac_f32_e32 v148, v45, v45
	s_waitcnt lgkmcnt(12)
	v_fma_f32 v65, v48, v170, -v228
	v_fma_f32 v49, v49, v173, -v229
	ds_read2st64_b32 v[190:191], v174 offset0:120 offset1:121
	v_fmac_f32_e32 v158, v65, v65
	v_fmac_f32_e32 v156, v49, v49
	s_waitcnt lgkmcnt(12)
	v_fma_f32 v48, v18, v0, -v234
	v_fma_f32 v47, v19, v136, -v235
	ds_read2st64_b32 v[182:183], v174 offset0:122 offset1:123
	v_fmac_f32_e32 v179, v48, v48
	v_fmac_f32_e32 v178, v47, v47
	s_waitcnt lgkmcnt(12)
	v_fma_f32 v127, v20, v137, -v236
	v_fma_f32 v126, v21, v138, -v237
	ds_read2st64_b32 v[192:193], v174 offset0:124 offset1:125
	v_fmac_f32_e32 v177, v127, v127
	v_fmac_f32_e32 v176, v126, v126
	s_waitcnt lgkmcnt(12)
; template <bool FIXED>
; __device__ __forceinline__ void df_unit(LAS char* lds, bf16_t* QKV, const float* gsub, float lam, float post, int b, int h, int qb, int wave0, float mfix2) {
;     ...
;         for (int d = 0; d < 8; ++d)
; #pragma unroll
;             for (int r = 0; r < 16; ++r) { const float v = o[d][r] * rli[r] - xch[(d * 16 + r) * 64]; o[d][r] = v; ssq[r] += v * v; }
; #pragma unroll
;         for (int r = 0; r < 16; ++r) { float s = ssq[r]; s = xsum<1>(s); s = xsum<2>(s); s = xsum<4>(s); s = xsum<8>(s); s = xsum<16>(s);
	v_fma_f32 v129, v22, v139, -v238
	v_fma_f32 v128, v23, v141, -v239
	ds_read2st64_b32 v[196:197], v174 offset0:126 offset1:127
	v_fmac_f32_e32 v175, v129, v129
	v_fmac_f32_e32 v171, v128, v128
	s_waitcnt lgkmcnt(12)
	v_fma_f32 v151, v24, v140, -v240
	v_fma_f32 v150, v25, v142, -v241
	v_fmac_f32_e32 v172, v151, v151
	v_fmac_f32_e32 v168, v150, v150
	s_waitcnt lgkmcnt(11)
	v_fma_f32 v153, v26, v144, -v242
	v_fma_f32 v152, v27, v146, -v243
	v_fmac_f32_e32 v166, v153, v153
	v_fmac_f32_e32 v161, v152, v152
	s_waitcnt lgkmcnt(10)
	v_fma_f32 v157, v28, v143, -v244
	v_fma_f32 v155, v29, v145, -v245
	v_fmac_f32_e32 v154, v157, v157
	v_fmac_f32_e32 v147, v155, v155
	s_waitcnt lgkmcnt(9)
	v_fma_f32 v160, v30, v167, -v246
	v_fma_f32 v159, v31, v169, -v247
	v_fmac_f32_e32 v149, v160, v160
	v_fmac_f32_e32 v148, v159, v159
	s_waitcnt lgkmcnt(8)
	v_fma_f32 v164, v32, v170, -v248
	v_fma_f32 v163, v33, v173, -v249
	v_fmac_f32_e32 v158, v164, v164
	v_fmac_f32_e32 v156, v163, v163
	s_waitcnt lgkmcnt(7)
	v_fma_f32 v162, v2, v0, -v180
	v_fma_f32 v136, v3, v136, -v181
	v_fmac_f32_e32 v179, v162, v162
	v_fmac_f32_e32 v178, v136, v136
	v_mov_b32_e32 v19, v1
	s_waitcnt lgkmcnt(6)
	v_fma_f32 v165, v4, v137, -v184
	v_fma_f32 v137, v5, v138, -v185
	v_fmac_f32_e32 v177, v165, v165
	v_fmac_f32_e32 v176, v137, v137
	s_waitcnt lgkmcnt(5)
	v_fma_f32 v139, v6, v139, -v186
	v_fma_f32 v138, v7, v141, -v187
	v_fmac_f32_e32 v175, v139, v139
	v_fmac_f32_e32 v171, v138, v138
	v_mov_b32_e32 v7, v1
	s_waitcnt lgkmcnt(4)
	v_fma_f32 v141, v8, v140, -v188
	v_fma_f32 v140, v9, v142, -v189
	v_fmac_f32_e32 v172, v141, v141
	v_fmac_f32_e32 v168, v140, v140
	s_waitcnt lgkmcnt(3)
	v_fma_f32 v144, v10, v144, -v190
	v_fma_f32 v142, v11, v146, -v191
	v_fmac_f32_e32 v166, v144, v144
	v_fmac_f32_e32 v161, v142, v142
	s_waitcnt lgkmcnt(2)
	v_fma_f32 v146, v12, v143, -v182
	v_fma_f32 v143, v13, v145, -v183
	v_fmac_f32_e32 v154, v146, v146
	v_fmac_f32_e32 v147, v143, v143
	s_waitcnt lgkmcnt(1)
	v_fma_f32 v167, v14, v167, -v192
	v_fma_f32 v145, v15, v169, -v193
	v_fmac_f32_e32 v149, v167, v167
	v_fmac_f32_e32 v148, v145, v145
	s_waitcnt lgkmcnt(0)
	v_fma_f32 v170, v16, v170, -v196
	v_fma_f32 v169, v17, v173, -v197
	v_fmac_f32_e32 v158, v170, v170
	v_fmac_f32_e32 v156, v169, v169
	ds_swizzle_b32 v196, v179 offset:swizzle(SWAP,1)
	ds_swizzle_b32 v197, v178 offset:swizzle(SWAP,1)
	ds_swizzle_b32 v198, v177 offset:swizzle(SWAP,1)
	ds_swizzle_b32 v199, v176 offset:swizzle(SWAP,1)
	ds_swizzle_b32 v200, v175 offset:swizzle(SWAP,1)
	ds_swizzle_b32 v201, v171 offset:swizzle(SWAP,1)
	ds_swizzle_b32 v206, v172 offset:swizzle(SWAP,1)
	ds_swizzle_b32 v207, v168 offset:swizzle(SWAP,1)
	ds_swizzle_b32 v208, v166 offset:swizzle(SWAP,1)
	ds_swizzle_b32 v209, v161 offset:swizzle(SWAP,1)
	ds_swizzle_b32 v210, v154 offset:swizzle(SWAP,1)
	s_waitcnt lgkmcnt(10)
	v_add_f32_e32 v180, v179, v196
	s_waitcnt lgkmcnt(9)
	v_add_f32_e32 v181, v178, v197
	s_waitcnt lgkmcnt(8)
	v_add_f32_e32 v182, v177, v198
	s_waitcnt lgkmcnt(7)
	v_add_f32_e32 v183, v176, v199
	s_waitcnt lgkmcnt(6)
	v_add_f32_e32 v184, v175, v200
	s_waitcnt lgkmcnt(5)
	v_add_f32_e32 v185, v171, v201
	ds_swizzle_b32 v211, v147 offset:swizzle(SWAP,1)
	ds_swizzle_b32 v212, v149 offset:swizzle(SWAP,1)
	ds_swizzle_b32 v213, v148 offset:swizzle(SWAP,1)
	ds_swizzle_b32 v214, v158 offset:swizzle(SWAP,1)
	ds_swizzle_b32 v215, v156 offset:swizzle(SWAP,1)
	s_waitcnt lgkmcnt(9)
	v_add_f32_e32 v186, v172, v206
	s_waitcnt lgkmcnt(8)
	v_add_f32_e32 v187, v168, v207
	s_waitcnt lgkmcnt(7)
	v_add_f32_e32 v188, v166, v208
	s_waitcnt lgkmcnt(6)
	v_add_f32_e32 v189, v161, v209
	s_waitcnt lgkmcnt(5)
	v_add_f32_e32 v190, v154, v210
	ds_swizzle_b32 v196, v180 offset:swizzle(SWAP,2)
	ds_swizzle_b32 v197, v181 offset:swizzle(SWAP,2)
	ds_swizzle_b32 v198, v182 offset:swizzle(SWAP,2)
	ds_swizzle_b32 v199, v183 offset:swizzle(SWAP,2)
	ds_swizzle_b32 v200, v184 offset:swizzle(SWAP,2)
	ds_swizzle_b32 v201, v185 offset:swizzle(SWAP,2)
	s_waitcnt lgkmcnt(10)
	v_add_f32_e32 v191, v147, v211
	s_waitcnt lgkmcnt(9)
	v_add_f32_e32 v192, v149, v212
	s_waitcnt lgkmcnt(8)
	v_add_f32_e32 v193, v148, v213
	s_waitcnt lgkmcnt(7)
	v_add_f32_e32 v194, v158, v214
	s_waitcnt lgkmcnt(6)
	v_add_f32_e32 v195, v156, v215
	ds_swizzle_b32 v206, v186 offset:swizzle(SWAP,2)
	ds_swizzle_b32 v207, v187 offset:swizzle(SWAP,2)
	ds_swizzle_b32 v208, v188 offset:swizzle(SWAP,2)
	ds_swizzle_b32 v209, v189 offset:swizzle(SWAP,2)
	ds_swizzle_b32 v210, v190 offset:swizzle(SWAP,2)
	s_waitcnt lgkmcnt(10)
	v_add_f32_e32 v180, v180, v196
	s_waitcnt lgkmcnt(9)
	v_add_f32_e32 v181, v181, v197
	s_waitcnt lgkmcnt(8)
	v_add_f32_e32 v182, v182, v198
	s_waitcnt lgkmcnt(7)
	v_add_f32_e32 v183, v183, v199
	s_waitcnt lgkmcnt(6)
	v_add_f32_e32 v184, v184, v200
	s_waitcnt lgkmcnt(5)
	v_add_f32_e32 v185, v185, v201
	ds_swizzle_b32 v211, v191 offset:swizzle(SWAP,2)
	ds_swizzle_b32 v212, v192 offset:swizzle(SWAP,2)
	ds_swizzle_b32 v213, v193 offset:swizzle(SWAP,2)
	ds_swizzle_b32 v214, v194 offset:swizzle(SWAP,2)
	ds_swizzle_b32 v215, v195 offset:swizzle(SWAP,2)
	s_waitcnt lgkmcnt(9)
	v_add_f32_e32 v186, v186, v206
	s_waitcnt lgkmcnt(8)
	v_add_f32_e32 v187, v187, v207
	s_waitcnt lgkmcnt(7)
	v_add_f32_e32 v188, v188, v208
	s_waitcnt lgkmcnt(6)
	v_add_f32_e32 v189, v189, v209
	s_waitcnt lgkmcnt(5)
	v_add_f32_e32 v190, v190, v210
	ds_swizzle_b32 v196, v180 offset:swizzle(SWAP,4)
	ds_swizzle_b32 v197, v181 offset:swizzle(SWAP,4)
	ds_swizzle_b32 v198, v182 offset:swizzle(SWAP,4)
	ds_swizzle_b32 v199, v183 offset:swizzle(SWAP,4)
	ds_swizzle_b32 v200, v184 offset:swizzle(SWAP,4)
	ds_swizzle_b32 v201, v185 offset:swizzle(SWAP,4)
	s_waitcnt lgkmcnt(10)
; template <bool FIXED>
; __device__ __forceinline__ void df_unit(LAS char* lds, bf16_t* QKV, const float* gsub, float lam, float post, int b, int h, int qb, int wave0, float mfix2) {
;     ...
;         for (int r = 0; r < 16; ++r) { float s = ssq[r]; s = xsum<1>(s); s = xsum<2>(s); s = xsum<4>(s); s = xsum<8>(s); s = xsum<16>(s);
	v_add_f32_e32 v191, v191, v211
	s_waitcnt lgkmcnt(9)
	v_add_f32_e32 v192, v192, v212
	s_waitcnt lgkmcnt(8)
	v_add_f32_e32 v193, v193, v213
	s_waitcnt lgkmcnt(7)
	v_add_f32_e32 v194, v194, v214
	s_waitcnt lgkmcnt(6)
	v_add_f32_e32 v195, v195, v215
	ds_swizzle_b32 v206, v186 offset:swizzle(SWAP,4)
	ds_swizzle_b32 v207, v187 offset:swizzle(SWAP,4)
	ds_swizzle_b32 v208, v188 offset:swizzle(SWAP,4)
	ds_swizzle_b32 v209, v189 offset:swizzle(SWAP,4)
	ds_swizzle_b32 v210, v190 offset:swizzle(SWAP,4)
	s_waitcnt lgkmcnt(10)
	v_add_f32_e32 v180, v180, v196
	s_waitcnt lgkmcnt(9)
	v_add_f32_e32 v181, v181, v197
	s_waitcnt lgkmcnt(8)
	v_add_f32_e32 v182, v182, v198
	s_waitcnt lgkmcnt(7)
	v_add_f32_e32 v183, v183, v199
	s_waitcnt lgkmcnt(6)
	v_add_f32_e32 v184, v184, v200
	s_waitcnt lgkmcnt(5)
	v_add_f32_e32 v185, v185, v201
	ds_swizzle_b32 v211, v191 offset:swizzle(SWAP,4)
	ds_swizzle_b32 v212, v192 offset:swizzle(SWAP,4)
	ds_swizzle_b32 v213, v193 offset:swizzle(SWAP,4)
	ds_swizzle_b32 v214, v194 offset:swizzle(SWAP,4)
	ds_swizzle_b32 v215, v195 offset:swizzle(SWAP,4)
	s_waitcnt lgkmcnt(9)
	v_add_f32_e32 v186, v186, v206
	s_waitcnt lgkmcnt(8)
	v_add_f32_e32 v187, v187, v207
	s_waitcnt lgkmcnt(7)
	v_add_f32_e32 v188, v188, v208
	s_waitcnt lgkmcnt(6)
	v_add_f32_e32 v189, v189, v209
	s_waitcnt lgkmcnt(5)
	v_add_f32_e32 v190, v190, v210
	ds_swizzle_b32 v196, v180 offset:swizzle(SWAP,8)
	ds_swizzle_b32 v197, v181 offset:swizzle(SWAP,8)
	ds_swizzle_b32 v198, v182 offset:swizzle(SWAP,8)
	ds_swizzle_b32 v199, v183 offset:swizzle(SWAP,8)
	ds_swizzle_b32 v200, v184 offset:swizzle(SWAP,8)
	ds_swizzle_b32 v201, v185 offset:swizzle(SWAP,8)
	s_waitcnt lgkmcnt(10)
	v_add_f32_e32 v191, v191, v211
	s_waitcnt lgkmcnt(9)
	v_add_f32_e32 v192, v192, v212
	s_waitcnt lgkmcnt(8)
	v_add_f32_e32 v193, v193, v213
	s_waitcnt lgkmcnt(7)
	v_add_f32_e32 v194, v194, v214
	s_waitcnt lgkmcnt(6)
	v_add_f32_e32 v195, v195, v215
	ds_swizzle_b32 v206, v186 offset:swizzle(SWAP,8)
	ds_swizzle_b32 v207, v187 offset:swizzle(SWAP,8)
	ds_swizzle_b32 v208, v188 offset:swizzle(SWAP,8)
	ds_swizzle_b32 v209, v189 offset:swizzle(SWAP,8)
	ds_swizzle_b32 v210, v190 offset:swizzle(SWAP,8)
	s_waitcnt lgkmcnt(10)
	v_add_f32_e32 v180, v180, v196
	s_waitcnt lgkmcnt(9)
	v_add_f32_e32 v181, v181, v197
	s_waitcnt lgkmcnt(8)
	v_add_f32_e32 v182, v182, v198
	s_waitcnt lgkmcnt(7)
	v_add_f32_e32 v183, v183, v199
	s_waitcnt lgkmcnt(6)
	v_add_f32_e32 v184, v184, v200
	s_waitcnt lgkmcnt(5)
	v_add_f32_e32 v185, v185, v201
	ds_swizzle_b32 v211, v191 offset:swizzle(SWAP,8)
	ds_swizzle_b32 v212, v192 offset:swizzle(SWAP,8)
	ds_swizzle_b32 v213, v193 offset:swizzle(SWAP,8)
	ds_swizzle_b32 v214, v194 offset:swizzle(SWAP,8)
	ds_swizzle_b32 v215, v195 offset:swizzle(SWAP,8)
	s_waitcnt lgkmcnt(9)
	v_add_f32_e32 v186, v186, v206
	s_waitcnt lgkmcnt(8)
	v_add_f32_e32 v187, v187, v207
	s_waitcnt lgkmcnt(7)
	v_add_f32_e32 v188, v188, v208
	s_waitcnt lgkmcnt(6)
	v_add_f32_e32 v189, v189, v209
	s_waitcnt lgkmcnt(5)
	v_add_f32_e32 v190, v190, v210
	ds_swizzle_b32 v196, v180 offset:swizzle(SWAP,16)
	ds_swizzle_b32 v197, v181 offset:swizzle(SWAP,16)
	ds_swizzle_b32 v198, v182 offset:swizzle(SWAP,16)
	ds_swizzle_b32 v199, v183 offset:swizzle(SWAP,16)
	ds_swizzle_b32 v200, v184 offset:swizzle(SWAP,16)
	ds_swizzle_b32 v201, v185 offset:swizzle(SWAP,16)
	s_waitcnt lgkmcnt(10)
	v_add_f32_e32 v191, v191, v211
	s_waitcnt lgkmcnt(9)
	v_add_f32_e32 v192, v192, v212
	s_waitcnt lgkmcnt(8)
	v_add_f32_e32 v193, v193, v213
	s_waitcnt lgkmcnt(7)
	v_add_f32_e32 v194, v194, v214
	s_waitcnt lgkmcnt(6)
	v_add_f32_e32 v195, v195, v215
	ds_swizzle_b32 v206, v186 offset:swizzle(SWAP,16)
	ds_swizzle_b32 v207, v187 offset:swizzle(SWAP,16)
	ds_swizzle_b32 v208, v188 offset:swizzle(SWAP,16)
	ds_swizzle_b32 v209, v189 offset:swizzle(SWAP,16)
	ds_swizzle_b32 v210, v190 offset:swizzle(SWAP,16)
	s_waitcnt lgkmcnt(10)
	v_add_f32_e32 v180, v180, v196
	s_waitcnt lgkmcnt(9)
	v_add_f32_e32 v181, v181, v197
	s_waitcnt lgkmcnt(8)
	v_add_f32_e32 v182, v182, v198
	s_waitcnt lgkmcnt(7)
	v_add_f32_e32 v183, v183, v199
	s_waitcnt lgkmcnt(6)
	v_add_f32_e32 v184, v184, v200
	s_waitcnt lgkmcnt(5)
	v_add_f32_e32 v185, v185, v201
	ds_swizzle_b32 v211, v191 offset:swizzle(SWAP,16)
	ds_swizzle_b32 v212, v192 offset:swizzle(SWAP,16)
	ds_swizzle_b32 v213, v193 offset:swizzle(SWAP,16)
	ds_swizzle_b32 v214, v194 offset:swizzle(SWAP,16)
	ds_swizzle_b32 v215, v195 offset:swizzle(SWAP,16)
	s_waitcnt lgkmcnt(9)
	v_add_f32_e32 v186, v186, v206
	s_waitcnt lgkmcnt(8)
	v_add_f32_e32 v187, v187, v207
	s_waitcnt lgkmcnt(7)
	v_add_f32_e32 v188, v188, v208
	s_waitcnt lgkmcnt(6)
	v_add_f32_e32 v189, v189, v209
	s_waitcnt lgkmcnt(5)
	v_add_f32_e32 v190, v190, v210
	s_waitcnt lgkmcnt(4)
	v_add_f32_e32 v191, v191, v211
	s_waitcnt lgkmcnt(3)
	v_add_f32_e32 v192, v192, v212
	s_waitcnt lgkmcnt(2)
	v_add_f32_e32 v193, v193, v213
	s_waitcnt lgkmcnt(1)
	v_add_f32_e32 v194, v194, v214
	s_waitcnt lgkmcnt(0)
; __device__ __forceinline__ int crow(int r, int hi) { return (r & 3) + 8 * (r >> 2) + 4 * hi; }
; __device__ __forceinline__ unsigned cvtpk(float lo, float hi) { unsigned r; asm volatile("v_cvt_pk_bf16_f32 %0, %1, %2" : "=v"(r) : "v"(lo), "v"(hi)); return r; }
; template <bool FIXED>
; __device__ __forceinline__ void df_unit(LAS char* lds, bf16_t* QKV, const float* gsub, float lam, float post, int b, int h, int qb, int wave0, float mfix2) {
;     ...
;         for (int r = 0; r < 16; ++r) { float s = ssq[r]; s = xsum<1>(s); s = xsum<2>(s); s = xsum<4>(s); s = xsum<8>(s); s = xsum<16>(s);
;             ssq[r] = post * __builtin_amdgcn_rsqf(s * (1.0f / 256.0f) + EPS); }
; #pragma unroll
;         for (int d = 0; d < 8; ++d) { const float g = gsub[d * 32 + r32];
; #pragma unroll
;             for (int r = 0; r < 16; ++r) *(unsigned short*)(rowsq + (size_t)crow(r, hi) * PITCH + d * 32 + r32) = (unsigned short)cvtpk(o[d][r] * ssq[r] * g, 0.f); }
	v_add_f32_e32 v195, v195, v215
	v_fmamk_f32 v180, v180, 0x3b800000, v223
	v_fmamk_f32 v181, v181, 0x3b800000, v223
	v_fmamk_f32 v182, v182, 0x3b800000, v223
	v_fmamk_f32 v183, v183, 0x3b800000, v223
	v_fmamk_f32 v184, v184, 0x3b800000, v223
	v_fmamk_f32 v185, v185, 0x3b800000, v223
	v_fmamk_f32 v186, v186, 0x3b800000, v223
	v_fmamk_f32 v187, v187, 0x3b800000, v223
	v_fmamk_f32 v188, v188, 0x3b800000, v223
	v_fmamk_f32 v189, v189, 0x3b800000, v223
	v_fmamk_f32 v190, v190, 0x3b800000, v223
	v_fmamk_f32 v191, v191, 0x3b800000, v223
	v_fmamk_f32 v192, v192, 0x3b800000, v223
	v_fmamk_f32 v193, v193, 0x3b800000, v223
	v_fmamk_f32 v194, v194, 0x3b800000, v223
	v_fmamk_f32 v195, v195, 0x3b800000, v223
	v_rsq_f32_e32 v180, v180
	v_rsq_f32_e32 v181, v181
	v_rsq_f32_e32 v182, v182
	v_rsq_f32_e32 v183, v183
	v_rsq_f32_e32 v184, v184
	v_rsq_f32_e32 v185, v185
	v_rsq_f32_e32 v186, v186
	v_rsq_f32_e32 v187, v187
	v_rsq_f32_e32 v188, v188
	v_rsq_f32_e32 v189, v189
	v_rsq_f32_e32 v190, v190
	v_rsq_f32_e32 v191, v191
	v_rsq_f32_e32 v192, v192
	v_rsq_f32_e32 v193, v193
	v_rsq_f32_e32 v194, v194
	v_rsq_f32_e32 v195, v195
	v_mul_f32_e32 v173, v232, v180
	v_mul_f32_e32 v174, v232, v181
	v_mul_f32_e32 v177, v232, v182
	v_mul_f32_e32 v176, v232, v183
	v_mul_f32_e32 v175, v232, v184
	v_mul_f32_e32 v171, v232, v185
	v_mul_f32_e32 v172, v232, v186
	v_mul_f32_e32 v168, v232, v187
	v_mul_f32_e32 v166, v232, v188
	v_mul_f32_e32 v161, v232, v189
	v_mul_f32_e32 v154, v232, v190
	v_mul_f32_e32 v147, v232, v191
	v_mul_f32_e32 v149, v232, v192
	v_mul_f32_e32 v148, v232, v193
	v_mul_f32_e32 v158, v232, v194
	v_mul_f32_e32 v156, v232, v195
	v_mul_f32_e32 v114, v114, v173
	v_lshlrev_b32_e32 v178, 2, v203
	global_load_dword v179, v178, s[68:69]
	v_mul_f32_e32 v98, v98, v174
	v_mul_f32_e32 v82, v82, v174
	v_mul_f32_e32 v66, v66, v174
	v_mul_f32_e32 v50, v50, v174
	v_mul_f32_e32 v34, v34, v174
	v_lshlrev_b32_e32 v0, 1, v203
	v_lshl_add_u64 v[2:3], s[8:9], 0, v[0:1]
	v_mul_f32_e32 v0, v135, v173
	s_waitcnt vmcnt(0)
	v_mul_f32_e32 v0, v0, v179
	v_cvt_pk_bf16_f32 v6, v0, v1
	v_mul_u32_u24_e32 v0, 0xc000, v202
	v_lshl_add_u64 v[4:5], v[2:3], 0, v[0:1]
	global_store_short v[4:5], v6, off
	v_mul_f32_e32 v6, v131, v174
	v_mul_f32_e32 v6, v6, v179
	v_cvt_pk_bf16_f32 v10, v6, v1
	v_or_b32_e32 v6, 0x3000, v0
	v_lshl_add_u64 v[8:9], v[2:3], 0, v[6:7]
	global_store_short v[8:9], v10, off
	v_mul_f32_e32 v8, v132, v177
	v_mul_f32_e32 v8, v8, v179
	v_cvt_pk_bf16_f32 v10, v8, v1
	v_add_co_u32_e32 v8, vcc, s0, v4
	s_mov_b32 s0, 0x9000
	s_nop 0
	v_addc_co_u32_e32 v9, vcc, 0, v5, vcc
	global_store_short v[8:9], v10, off
	v_mul_f32_e32 v10, v117, v176
	v_mul_f32_e32 v10, v10, v179
	v_cvt_pk_bf16_f32 v12, v10, v1
	v_add_co_u32_e32 v10, vcc, s0, v4
	s_mov_b32 s0, 0x18000
	s_nop 0
	v_addc_co_u32_e32 v11, vcc, 0, v5, vcc
	global_store_short v[10:11], v12, off
	v_mul_f32_e32 v12, v130, v175
	v_mul_f32_e32 v12, v12, v179
	v_cvt_pk_bf16_f32 v14, v12, v1
	v_add_co_u32_e32 v12, vcc, s0, v4
	s_mov_b32 s0, 0x1b000
	s_nop 0
	v_addc_co_u32_e32 v13, vcc, 0, v5, vcc
	global_store_short v[12:13], v14, off
	v_mul_f32_e32 v14, v115, v171
	v_mul_f32_e32 v14, v14, v179
	v_cvt_pk_bf16_f32 v16, v14, v1
	v_add_co_u32_e32 v14, vcc, s0, v4
	s_mov_b32 s0, 0x1e000
	s_nop 0
	v_addc_co_u32_e32 v15, vcc, 0, v5, vcc
	global_store_short v[14:15], v16, off
	v_mul_f32_e32 v16, v134, v172
	v_mul_f32_e32 v16, v16, v179
	v_cvt_pk_bf16_f32 v18, v16, v1
	v_add_co_u32_e32 v16, vcc, s0, v4
	s_mov_b32 s0, 0x36000
	s_nop 0
	v_addc_co_u32_e32 v17, vcc, 0, v5, vcc
	global_store_short v[16:17], v18, off
	v_mul_f32_e32 v18, v119, v168
	v_mul_f32_e32 v18, v18, v179
	v_cvt_pk_bf16_f32 v22, v18, v1
	v_or_b32_e32 v18, 0x21000, v0
	v_lshl_add_u64 v[20:21], v[2:3], 0, v[18:19]
	global_store_short v[20:21], v22, off
	v_mul_f32_e32 v20, v133, v166
	v_mul_f32_e32 v20, v20, v179
	v_cvt_pk_bf16_f32 v24, v20, v1
	v_or_b32_e32 v20, 0x30000, v0
	v_mov_b32_e32 v21, v1
	v_lshl_add_u64 v[22:23], v[2:3], 0, v[20:21]
	global_store_short v[22:23], v24, off
	v_mul_f32_e32 v22, v120, v161
	v_mul_f32_e32 v22, v22, v179
	v_cvt_pk_bf16_f32 v26, v22, v1
	v_or_b32_e32 v22, 0x33000, v0
	v_mov_b32_e32 v23, v1
	v_lshl_add_u64 v[24:25], v[2:3], 0, v[22:23]
	global_store_short v[24:25], v26, off
	v_mul_f32_e32 v24, v123, v154
	v_mul_f32_e32 v24, v24, v179
	v_cvt_pk_bf16_f32 v26, v24, v1
	v_add_co_u32_e32 v24, vcc, s0, v4
	s_mov_b32 s0, 0x39000
	s_nop 0
	v_addc_co_u32_e32 v25, vcc, 0, v5, vcc
	global_store_short v[24:25], v26, off
	v_mul_f32_e32 v26, v118, v147
	v_mul_f32_e32 v26, v26, v179
	v_cvt_pk_bf16_f32 v28, v26, v1
	v_add_co_u32_e32 v26, vcc, s0, v4
	s_mov_b32 s0, 0x48000
	s_nop 0
	v_addc_co_u32_e32 v27, vcc, 0, v5, vcc
	global_store_short v[26:27], v28, off
	v_mul_f32_e32 v28, v122, v149
	v_mul_f32_e32 v28, v28, v179
	v_cvt_pk_bf16_f32 v30, v28, v1
	v_add_co_u32_e32 v28, vcc, s0, v4
	s_mov_b32 s0, 0x4b000
	s_nop 0
	v_addc_co_u32_e32 v29, vcc, 0, v5, vcc
	global_store_short v[28:29], v30, off
	v_mul_f32_e32 v30, v116, v148
	v_mul_f32_e32 v30, v30, v179
	v_cvt_pk_bf16_f32 v32, v30, v1
	v_add_co_u32_e32 v30, vcc, s0, v4
	s_mov_b32 s0, 0x4e000
	s_nop 0
	v_addc_co_u32_e32 v31, vcc, 0, v5, vcc
	global_store_short v[30:31], v32, off
	v_mul_f32_e32 v32, v124, v158
	v_mul_f32_e32 v32, v179, v32
	v_cvt_pk_bf16_f32 v115, v32, v1
	v_add_co_u32_e32 v32, vcc, s0, v4
	v_or_b32_e32 v0, 0x51000, v0
	s_nop 0
	v_addc_co_u32_e32 v33, vcc, 0, v5, vcc
	global_store_short v[32:33], v115, off
	v_mul_f32_e32 v115, v121, v156
	v_mul_f32_e32 v115, v179, v115
	v_cvt_pk_bf16_f32 v115, v115, v1
	global_load_dword v118, v178, s[68:69] offset:128
	v_lshl_add_u64 v[116:117], v[2:3], 0, v[0:1]
	global_store_short v[116:117], v115, off
	v_lshl_add_u64 v[116:117], v[2:3], 0, 64
	s_mov_b64 s[0:1], 0xc0
	s_waitcnt vmcnt(1)
; __device__ __forceinline__ int crow(int r, int hi) { return (r & 3) + 8 * (r >> 2) + 4 * hi; }
; __device__ __forceinline__ unsigned cvtpk(float lo, float hi) { unsigned r; asm volatile("v_cvt_pk_bf16_f32 %0, %1, %2" : "=v"(r) : "v"(lo), "v"(hi)); return r; }
; template <bool FIXED>
; __device__ __forceinline__ void df_unit(LAS char* lds, bf16_t* QKV, const float* gsub, float lam, float post, int b, int h, int qb, int wave0, float mfix2) {
;     ...
;         for (int d = 0; d < 8; ++d) { const float g = gsub[d * 32 + r32];
; #pragma unroll
;             for (int r = 0; r < 16; ++r) *(unsigned short*)(rowsq + (size_t)crow(r, hi) * PITCH + d * 32 + r32) = (unsigned short)cvtpk(o[d][r] * ssq[r] * g, 0.f); }
	v_mul_f32_e32 v114, v114, v118
	v_cvt_pk_bf16_f32 v114, v114, v1
	v_mul_f32_e32 v98, v98, v118
	global_store_short v[4:5], v114, off offset:64
	v_cvt_pk_bf16_f32 v98, v98, v1
	v_lshl_add_u64 v[114:115], v[116:117], 0, v[6:7]
	global_store_short v[114:115], v98, off
	v_mul_f32_e32 v98, v100, v177
	v_mul_f32_e32 v98, v98, v118
	v_cvt_pk_bf16_f32 v98, v98, v1
	global_store_short v[8:9], v98, off offset:64
	v_mul_f32_e32 v98, v99, v176
	v_mul_f32_e32 v98, v98, v118
	v_cvt_pk_bf16_f32 v98, v98, v1
	global_store_short v[10:11], v98, off offset:64
	v_mul_f32_e32 v98, v102, v175
	v_mul_f32_e32 v98, v98, v118
	v_cvt_pk_bf16_f32 v98, v98, v1
	global_store_short v[12:13], v98, off offset:64
	v_mul_f32_e32 v98, v101, v171
	v_mul_f32_e32 v98, v98, v118
	v_cvt_pk_bf16_f32 v98, v98, v1
	global_store_short v[14:15], v98, off offset:64
	v_mul_f32_e32 v98, v104, v172
	v_mul_f32_e32 v98, v98, v118
	v_cvt_pk_bf16_f32 v98, v98, v1
	global_store_short v[16:17], v98, off offset:64
	v_mul_f32_e32 v98, v103, v168
	v_mul_f32_e32 v98, v98, v118
	v_cvt_pk_bf16_f32 v100, v98, v1
	v_lshl_add_u64 v[98:99], v[116:117], 0, v[18:19]
	global_store_short v[98:99], v100, off
	v_mul_f32_e32 v98, v106, v166
	v_mul_f32_e32 v98, v98, v118
	v_cvt_pk_bf16_f32 v100, v98, v1
	v_lshl_add_u64 v[98:99], v[116:117], 0, v[20:21]
	global_store_short v[98:99], v100, off
	v_mul_f32_e32 v98, v105, v161
	v_mul_f32_e32 v98, v98, v118
	v_cvt_pk_bf16_f32 v100, v98, v1
	v_lshl_add_u64 v[98:99], v[116:117], 0, v[22:23]
	global_store_short v[98:99], v100, off
	v_mul_f32_e32 v98, v108, v154
	v_mul_f32_e32 v98, v98, v118
	v_cvt_pk_bf16_f32 v98, v98, v1
	global_store_short v[24:25], v98, off offset:64
	v_mul_f32_e32 v98, v107, v147
	v_mul_f32_e32 v98, v98, v118
	v_cvt_pk_bf16_f32 v98, v98, v1
	global_store_short v[26:27], v98, off offset:64
	v_mul_f32_e32 v98, v110, v149
	v_mul_f32_e32 v98, v98, v118
	v_cvt_pk_bf16_f32 v98, v98, v1
	global_store_short v[28:29], v98, off offset:64
	v_mul_f32_e32 v98, v109, v148
	v_mul_f32_e32 v98, v98, v118
	v_cvt_pk_bf16_f32 v98, v98, v1
	global_store_short v[30:31], v98, off offset:64
	v_mul_f32_e32 v98, v112, v158
	v_mul_f32_e32 v98, v98, v118
	v_cvt_pk_bf16_f32 v98, v98, v1
	global_store_short v[32:33], v98, off offset:64
	v_mul_f32_e32 v98, v113, v156
	v_mul_f32_e32 v98, v98, v118
	v_cvt_pk_bf16_f32 v100, v98, v1
	global_load_dword v102, v178, s[68:69] offset:256
	v_lshl_add_u64 v[98:99], v[116:117], 0, v[0:1]
	global_store_short v[98:99], v100, off
	v_mul_f32_e32 v100, v111, v173
	v_lshl_add_u64 v[98:99], v[2:3], 0, s[28:29]
	s_waitcnt vmcnt(1)
	v_mul_f32_e32 v100, v100, v102
	v_cvt_pk_bf16_f32 v100, v100, v1
	v_mul_f32_e32 v82, v82, v102
	global_store_short v[4:5], v100, off offset:128
	v_cvt_pk_bf16_f32 v82, v82, v1
	v_lshl_add_u64 v[100:101], v[98:99], 0, v[6:7]
	global_store_short v[100:101], v82, off
	v_mul_f32_e32 v82, v84, v177
	v_mul_f32_e32 v82, v82, v102
	v_cvt_pk_bf16_f32 v82, v82, v1
	global_store_short v[8:9], v82, off offset:128
	v_mul_f32_e32 v82, v83, v176
	v_mul_f32_e32 v82, v82, v102
	v_cvt_pk_bf16_f32 v82, v82, v1
	global_store_short v[10:11], v82, off offset:128
	v_mul_f32_e32 v82, v86, v175
	v_mul_f32_e32 v82, v82, v102
	v_cvt_pk_bf16_f32 v82, v82, v1
	global_store_short v[12:13], v82, off offset:128
	v_mul_f32_e32 v82, v85, v171
	v_mul_f32_e32 v82, v82, v102
	v_cvt_pk_bf16_f32 v82, v82, v1
	global_store_short v[14:15], v82, off offset:128
	v_mul_f32_e32 v82, v88, v172
	v_mul_f32_e32 v82, v82, v102
	v_cvt_pk_bf16_f32 v82, v82, v1
	global_store_short v[16:17], v82, off offset:128
	v_mul_f32_e32 v82, v87, v168
	v_mul_f32_e32 v82, v82, v102
	v_cvt_pk_bf16_f32 v84, v82, v1
	v_lshl_add_u64 v[82:83], v[98:99], 0, v[18:19]
	global_store_short v[82:83], v84, off
	v_mul_f32_e32 v82, v90, v166
	v_mul_f32_e32 v82, v82, v102
	v_cvt_pk_bf16_f32 v84, v82, v1
	v_lshl_add_u64 v[82:83], v[98:99], 0, v[20:21]
	global_store_short v[82:83], v84, off
	v_mul_f32_e32 v82, v89, v161
	v_mul_f32_e32 v82, v82, v102
	v_cvt_pk_bf16_f32 v84, v82, v1
	v_lshl_add_u64 v[82:83], v[98:99], 0, v[22:23]
	global_store_short v[82:83], v84, off
	v_mul_f32_e32 v82, v92, v154
	v_mul_f32_e32 v82, v82, v102
	v_cvt_pk_bf16_f32 v82, v82, v1
	global_store_short v[24:25], v82, off offset:128
	v_mul_f32_e32 v82, v91, v147
	v_mul_f32_e32 v82, v82, v102
	v_cvt_pk_bf16_f32 v82, v82, v1
	global_store_short v[26:27], v82, off offset:128
	v_mul_f32_e32 v82, v94, v149
	v_mul_f32_e32 v82, v82, v102
	v_cvt_pk_bf16_f32 v82, v82, v1
	global_store_short v[28:29], v82, off offset:128
	v_mul_f32_e32 v82, v93, v148
	v_mul_f32_e32 v82, v82, v102
	v_cvt_pk_bf16_f32 v82, v82, v1
	global_store_short v[30:31], v82, off offset:128
	v_mul_f32_e32 v82, v125, v158
	v_mul_f32_e32 v82, v82, v102
	v_cvt_pk_bf16_f32 v82, v82, v1
	global_store_short v[32:33], v82, off offset:128
	v_mul_f32_e32 v82, v96, v156
	v_mul_f32_e32 v82, v82, v102
	v_cvt_pk_bf16_f32 v84, v82, v1
	global_load_dword v86, v178, s[68:69] offset:384
	v_lshl_add_u64 v[82:83], v[98:99], 0, v[0:1]
	global_store_short v[82:83], v84, off
	v_mul_f32_e32 v84, v95, v173
	v_lshl_add_u64 v[82:83], v[2:3], 0, s[0:1]
	s_mov_b64 s[0:1], 0x100
	s_waitcnt vmcnt(1)
; __device__ __forceinline__ int crow(int r, int hi) { return (r & 3) + 8 * (r >> 2) + 4 * hi; }
; __device__ __forceinline__ unsigned cvtpk(float lo, float hi) { unsigned r; asm volatile("v_cvt_pk_bf16_f32 %0, %1, %2" : "=v"(r) : "v"(lo), "v"(hi)); return r; }
; template <bool FIXED>
; __device__ __forceinline__ void df_unit(LAS char* lds, bf16_t* QKV, const float* gsub, float lam, float post, int b, int h, int qb, int wave0, float mfix2) {
;     ...
;         for (int d = 0; d < 8; ++d) { const float g = gsub[d * 32 + r32];
; #pragma unroll
;             for (int r = 0; r < 16; ++r) *(unsigned short*)(rowsq + (size_t)crow(r, hi) * PITCH + d * 32 + r32) = (unsigned short)cvtpk(o[d][r] * ssq[r] * g, 0.f); }
	v_mul_f32_e32 v84, v84, v86
	v_cvt_pk_bf16_f32 v84, v84, v1
	v_mul_f32_e32 v66, v66, v86
	global_store_short v[4:5], v84, off offset:192
	v_cvt_pk_bf16_f32 v66, v66, v1
	v_lshl_add_u64 v[84:85], v[82:83], 0, v[6:7]
	global_store_short v[84:85], v66, off
	v_mul_f32_e32 v66, v68, v177
	v_mul_f32_e32 v66, v66, v86
	v_cvt_pk_bf16_f32 v66, v66, v1
	global_store_short v[8:9], v66, off offset:192
	v_mul_f32_e32 v66, v67, v176
	v_mul_f32_e32 v66, v66, v86
	v_cvt_pk_bf16_f32 v66, v66, v1
	global_store_short v[10:11], v66, off offset:192
	v_mul_f32_e32 v66, v70, v175
	v_mul_f32_e32 v66, v66, v86
	v_cvt_pk_bf16_f32 v66, v66, v1
	global_store_short v[12:13], v66, off offset:192
	v_mul_f32_e32 v66, v69, v171
	v_mul_f32_e32 v66, v66, v86
	v_cvt_pk_bf16_f32 v66, v66, v1
	global_store_short v[14:15], v66, off offset:192
	v_mul_f32_e32 v66, v72, v172
	v_mul_f32_e32 v66, v66, v86
	v_cvt_pk_bf16_f32 v66, v66, v1
	global_store_short v[16:17], v66, off offset:192
	v_mul_f32_e32 v66, v71, v168
	v_mul_f32_e32 v66, v66, v86
	v_cvt_pk_bf16_f32 v68, v66, v1
	v_lshl_add_u64 v[66:67], v[82:83], 0, v[18:19]
	global_store_short v[66:67], v68, off
	v_mul_f32_e32 v66, v74, v166
	v_mul_f32_e32 v66, v66, v86
	v_cvt_pk_bf16_f32 v68, v66, v1
	v_lshl_add_u64 v[66:67], v[82:83], 0, v[20:21]
	global_store_short v[66:67], v68, off
	v_mul_f32_e32 v66, v73, v161
	v_mul_f32_e32 v66, v66, v86
	v_cvt_pk_bf16_f32 v68, v66, v1
	v_lshl_add_u64 v[66:67], v[82:83], 0, v[22:23]
	global_store_short v[66:67], v68, off
	v_mul_f32_e32 v66, v76, v154
	v_mul_f32_e32 v66, v66, v86
	v_cvt_pk_bf16_f32 v66, v66, v1
	global_store_short v[24:25], v66, off offset:192
	v_mul_f32_e32 v66, v75, v147
	v_mul_f32_e32 v66, v66, v86
	v_cvt_pk_bf16_f32 v66, v66, v1
	global_store_short v[26:27], v66, off offset:192
	v_mul_f32_e32 v66, v78, v149
	v_mul_f32_e32 v66, v66, v86
	v_cvt_pk_bf16_f32 v66, v66, v1
	global_store_short v[28:29], v66, off offset:192
	v_mul_f32_e32 v66, v77, v148
	v_mul_f32_e32 v66, v66, v86
	v_cvt_pk_bf16_f32 v66, v66, v1
	global_store_short v[30:31], v66, off offset:192
	v_mul_f32_e32 v66, v97, v158
	v_mul_f32_e32 v66, v66, v86
	v_cvt_pk_bf16_f32 v66, v66, v1
	global_store_short v[32:33], v66, off offset:192
	v_mul_f32_e32 v66, v80, v156
	v_mul_f32_e32 v66, v66, v86
	v_cvt_pk_bf16_f32 v68, v66, v1
	global_load_dword v70, v178, s[68:69] offset:512
	v_lshl_add_u64 v[66:67], v[82:83], 0, v[0:1]
	global_store_short v[66:67], v68, off
	v_mul_f32_e32 v68, v79, v173
	v_lshl_add_u64 v[66:67], v[2:3], 0, s[0:1]
	s_mov_b64 s[0:1], 0x140
	s_waitcnt vmcnt(1)
	v_mul_f32_e32 v68, v68, v70
	v_cvt_pk_bf16_f32 v68, v68, v1
	v_mul_f32_e32 v50, v50, v70
	global_store_short v[4:5], v68, off offset:256
	v_cvt_pk_bf16_f32 v50, v50, v1
	v_lshl_add_u64 v[68:69], v[66:67], 0, v[6:7]
	global_store_short v[68:69], v50, off
	v_mul_f32_e32 v50, v52, v177
	v_mul_f32_e32 v50, v50, v70
	v_cvt_pk_bf16_f32 v50, v50, v1
	global_store_short v[8:9], v50, off offset:256
	v_mul_f32_e32 v50, v51, v176
	v_mul_f32_e32 v50, v50, v70
	v_cvt_pk_bf16_f32 v50, v50, v1
	global_store_short v[10:11], v50, off offset:256
	v_mul_f32_e32 v50, v54, v175
	v_mul_f32_e32 v50, v50, v70
	v_cvt_pk_bf16_f32 v50, v50, v1
	global_store_short v[12:13], v50, off offset:256
	v_mul_f32_e32 v50, v53, v171
	v_mul_f32_e32 v50, v50, v70
	v_cvt_pk_bf16_f32 v50, v50, v1
	global_store_short v[14:15], v50, off offset:256
	v_mul_f32_e32 v50, v56, v172
	v_mul_f32_e32 v50, v50, v70
	v_cvt_pk_bf16_f32 v50, v50, v1
	global_store_short v[16:17], v50, off offset:256
	v_mul_f32_e32 v50, v55, v168
	v_mul_f32_e32 v50, v50, v70
	v_cvt_pk_bf16_f32 v52, v50, v1
	v_lshl_add_u64 v[50:51], v[66:67], 0, v[18:19]
	global_store_short v[50:51], v52, off
	v_mul_f32_e32 v50, v58, v166
	v_mul_f32_e32 v50, v50, v70
	v_cvt_pk_bf16_f32 v52, v50, v1
	v_lshl_add_u64 v[50:51], v[66:67], 0, v[20:21]
	global_store_short v[50:51], v52, off
	v_mul_f32_e32 v50, v57, v161
	v_mul_f32_e32 v50, v50, v70
	v_cvt_pk_bf16_f32 v52, v50, v1
	v_lshl_add_u64 v[50:51], v[66:67], 0, v[22:23]
	global_store_short v[50:51], v52, off
	v_mul_f32_e32 v50, v60, v154
	v_mul_f32_e32 v50, v50, v70
	v_cvt_pk_bf16_f32 v50, v50, v1
	global_store_short v[24:25], v50, off offset:256
	v_mul_f32_e32 v50, v59, v147
	v_mul_f32_e32 v50, v50, v70
	v_cvt_pk_bf16_f32 v50, v50, v1
	global_store_short v[26:27], v50, off offset:256
	v_mul_f32_e32 v50, v62, v149
	v_mul_f32_e32 v50, v50, v70
	v_cvt_pk_bf16_f32 v50, v50, v1
	global_store_short v[28:29], v50, off offset:256
	v_mul_f32_e32 v50, v61, v148
	v_mul_f32_e32 v50, v50, v70
	v_cvt_pk_bf16_f32 v50, v50, v1
	global_store_short v[30:31], v50, off offset:256
	v_mul_f32_e32 v50, v81, v158
	v_mul_f32_e32 v50, v50, v70
	v_cvt_pk_bf16_f32 v50, v50, v1
	global_store_short v[32:33], v50, off offset:256
	v_mul_f32_e32 v50, v64, v156
	v_mul_f32_e32 v50, v50, v70
	v_cvt_pk_bf16_f32 v52, v50, v1
	global_load_dword v54, v178, s[68:69] offset:640
	v_lshl_add_u64 v[50:51], v[66:67], 0, v[0:1]
	global_store_short v[50:51], v52, off
	v_mul_f32_e32 v52, v63, v173
	v_lshl_add_u64 v[50:51], v[2:3], 0, s[0:1]
	s_mov_b64 s[0:1], 0x180
	s_waitcnt vmcnt(1)
; __device__ __forceinline__ int crow(int r, int hi) { return (r & 3) + 8 * (r >> 2) + 4 * hi; }
; __device__ __forceinline__ unsigned cvtpk(float lo, float hi) { unsigned r; asm volatile("v_cvt_pk_bf16_f32 %0, %1, %2" : "=v"(r) : "v"(lo), "v"(hi)); return r; }
; template <bool FIXED>
; __device__ __forceinline__ void df_unit(LAS char* lds, bf16_t* QKV, const float* gsub, float lam, float post, int b, int h, int qb, int wave0, float mfix2) {
;     ...
;         for (int d = 0; d < 8; ++d) { const float g = gsub[d * 32 + r32];
; #pragma unroll
;             for (int r = 0; r < 16; ++r) *(unsigned short*)(rowsq + (size_t)crow(r, hi) * PITCH + d * 32 + r32) = (unsigned short)cvtpk(o[d][r] * ssq[r] * g, 0.f); }
	v_mul_f32_e32 v52, v52, v54
	v_cvt_pk_bf16_f32 v52, v52, v1
	v_mul_f32_e32 v34, v34, v54
	global_store_short v[4:5], v52, off offset:320
	v_cvt_pk_bf16_f32 v34, v34, v1
	v_lshl_add_u64 v[52:53], v[50:51], 0, v[6:7]
	global_store_short v[52:53], v34, off
	v_mul_f32_e32 v34, v36, v177
	v_mul_f32_e32 v34, v34, v54
	v_cvt_pk_bf16_f32 v34, v34, v1
	global_store_short v[8:9], v34, off offset:320
	v_mul_f32_e32 v34, v35, v176
	v_mul_f32_e32 v34, v34, v54
	v_cvt_pk_bf16_f32 v34, v34, v1
	global_store_short v[10:11], v34, off offset:320
	v_mul_f32_e32 v34, v38, v175
	v_mul_f32_e32 v34, v34, v54
	v_cvt_pk_bf16_f32 v34, v34, v1
	global_store_short v[12:13], v34, off offset:320
	v_mul_f32_e32 v34, v37, v171
	v_mul_f32_e32 v34, v34, v54
	v_cvt_pk_bf16_f32 v34, v34, v1
	global_store_short v[14:15], v34, off offset:320
	v_mul_f32_e32 v34, v40, v172
	v_mul_f32_e32 v34, v34, v54
	v_cvt_pk_bf16_f32 v34, v34, v1
	global_store_short v[16:17], v34, off offset:320
	v_mul_f32_e32 v34, v39, v168
	v_mul_f32_e32 v34, v34, v54
	v_cvt_pk_bf16_f32 v36, v34, v1
	v_lshl_add_u64 v[34:35], v[50:51], 0, v[18:19]
	global_store_short v[34:35], v36, off
	v_mul_f32_e32 v34, v42, v166
	v_mul_f32_e32 v34, v34, v54
	v_cvt_pk_bf16_f32 v36, v34, v1
	v_lshl_add_u64 v[34:35], v[50:51], 0, v[20:21]
	global_store_short v[34:35], v36, off
	v_mul_f32_e32 v34, v41, v161
	v_mul_f32_e32 v34, v34, v54
	v_cvt_pk_bf16_f32 v36, v34, v1
	v_lshl_add_u64 v[34:35], v[50:51], 0, v[22:23]
	global_store_short v[34:35], v36, off
	v_mul_f32_e32 v34, v44, v154
	v_mul_f32_e32 v34, v34, v54
	v_cvt_pk_bf16_f32 v34, v34, v1
	global_store_short v[24:25], v34, off offset:320
	v_mul_f32_e32 v34, v43, v147
	v_mul_f32_e32 v34, v34, v54
	v_cvt_pk_bf16_f32 v34, v34, v1
	global_store_short v[26:27], v34, off offset:320
	v_mul_f32_e32 v34, v46, v149
	v_mul_f32_e32 v34, v34, v54
	v_cvt_pk_bf16_f32 v34, v34, v1
	global_store_short v[28:29], v34, off offset:320
	v_mul_f32_e32 v34, v45, v148
	v_mul_f32_e32 v34, v34, v54
	v_cvt_pk_bf16_f32 v34, v34, v1
	global_store_short v[30:31], v34, off offset:320
	v_mul_f32_e32 v34, v65, v158
	v_mul_f32_e32 v34, v34, v54
	v_cvt_pk_bf16_f32 v34, v34, v1
	global_store_short v[32:33], v34, off offset:320
	v_mul_f32_e32 v34, v49, v156
	v_mul_f32_e32 v34, v34, v54
	v_cvt_pk_bf16_f32 v36, v34, v1
	global_load_dword v38, v178, s[68:69] offset:768
	v_lshl_add_u64 v[34:35], v[50:51], 0, v[0:1]
	global_store_short v[34:35], v36, off
	v_mul_f32_e32 v36, v48, v173
	v_lshl_add_u64 v[34:35], v[2:3], 0, s[0:1]
	s_mov_b64 s[0:1], 0x1c0
	v_lshl_add_u64 v[2:3], v[2:3], 0, s[0:1]
	s_waitcnt vmcnt(1)
; __device__ __forceinline__ int crow(int r, int hi) { return (r & 3) + 8 * (r >> 2) + 4 * hi; }
; __device__ __forceinline__ unsigned cvtpk(float lo, float hi) { unsigned r; asm volatile("v_cvt_pk_bf16_f32 %0, %1, %2" : "=v"(r) : "v"(lo), "v"(hi)); return r; }
; template <bool FIXED>
; __device__ __forceinline__ void df_unit(LAS char* lds, bf16_t* QKV, const float* gsub, float lam, float post, int b, int h, int qb, int wave0, float mfix2) {
;     ...
;         for (int d = 0; d < 8; ++d) { const float g = gsub[d * 32 + r32];
; #pragma unroll
;             for (int r = 0; r < 16; ++r) *(unsigned short*)(rowsq + (size_t)crow(r, hi) * PITCH + d * 32 + r32) = (unsigned short)cvtpk(o[d][r] * ssq[r] * g, 0.f); }
	v_mul_f32_e32 v36, v36, v38
	v_cvt_pk_bf16_f32 v36, v36, v1
	global_store_short v[4:5], v36, off offset:384
	v_mul_f32_e32 v36, v47, v174
	v_mul_f32_e32 v36, v36, v38
	v_cvt_pk_bf16_f32 v39, v36, v1
	v_lshl_add_u64 v[36:37], v[34:35], 0, v[6:7]
	global_store_short v[36:37], v39, off
	v_mul_f32_e32 v36, v127, v177
	v_mul_f32_e32 v36, v36, v38
	v_cvt_pk_bf16_f32 v36, v36, v1
	global_store_short v[8:9], v36, off offset:384
	v_mul_f32_e32 v36, v126, v176
	v_mul_f32_e32 v36, v36, v38
	v_cvt_pk_bf16_f32 v36, v36, v1
	global_store_short v[10:11], v36, off offset:384
	v_mul_f32_e32 v36, v129, v175
	v_mul_f32_e32 v36, v36, v38
	v_cvt_pk_bf16_f32 v36, v36, v1
	global_store_short v[12:13], v36, off offset:384
	v_mul_f32_e32 v36, v128, v171
	v_mul_f32_e32 v36, v36, v38
	v_cvt_pk_bf16_f32 v36, v36, v1
	global_store_short v[14:15], v36, off offset:384
	v_mul_f32_e32 v36, v151, v172
	v_mul_f32_e32 v36, v36, v38
	v_cvt_pk_bf16_f32 v36, v36, v1
	global_store_short v[16:17], v36, off offset:384
	v_mul_f32_e32 v36, v150, v168
	v_mul_f32_e32 v36, v36, v38
	v_cvt_pk_bf16_f32 v39, v36, v1
	v_lshl_add_u64 v[36:37], v[34:35], 0, v[18:19]
	global_store_short v[36:37], v39, off
	v_mul_f32_e32 v36, v153, v166
	v_mul_f32_e32 v36, v36, v38
	v_cvt_pk_bf16_f32 v39, v36, v1
	v_lshl_add_u64 v[36:37], v[34:35], 0, v[20:21]
	global_store_short v[36:37], v39, off
	v_mul_f32_e32 v36, v152, v161
	v_mul_f32_e32 v36, v36, v38
	v_cvt_pk_bf16_f32 v39, v36, v1
	v_lshl_add_u64 v[36:37], v[34:35], 0, v[22:23]
	global_store_short v[36:37], v39, off
	v_mul_f32_e32 v36, v157, v154
	v_mul_f32_e32 v36, v36, v38
	v_cvt_pk_bf16_f32 v36, v36, v1
	global_store_short v[24:25], v36, off offset:384
	v_mul_f32_e32 v36, v155, v147
	v_mul_f32_e32 v36, v36, v38
	v_cvt_pk_bf16_f32 v36, v36, v1
	global_store_short v[26:27], v36, off offset:384
	v_mul_f32_e32 v36, v160, v149
	v_mul_f32_e32 v36, v36, v38
	v_cvt_pk_bf16_f32 v36, v36, v1
	global_store_short v[28:29], v36, off offset:384
	v_mul_f32_e32 v36, v159, v148
	v_mul_f32_e32 v36, v36, v38
	v_cvt_pk_bf16_f32 v36, v36, v1
	global_store_short v[30:31], v36, off offset:384
	v_mul_f32_e32 v36, v164, v158
	v_mul_f32_e32 v36, v36, v38
	v_cvt_pk_bf16_f32 v36, v36, v1
	global_store_short v[32:33], v36, off offset:384
	v_mul_f32_e32 v36, v163, v156
	v_mul_f32_e32 v36, v36, v38
	v_lshl_add_u64 v[34:35], v[34:35], 0, v[0:1]
	v_cvt_pk_bf16_f32 v36, v36, v1
	global_store_short v[34:35], v36, off
	global_load_dword v34, v178, s[68:69] offset:896
	v_mul_f32_e32 v35, v162, v173
	s_waitcnt vmcnt(0)
	v_mul_f32_e32 v35, v35, v34
	v_cvt_pk_bf16_f32 v35, v35, v1
	global_store_short v[4:5], v35, off offset:448
	v_mul_f32_e32 v4, v136, v174
	v_mul_f32_e32 v4, v4, v34
	v_cvt_pk_bf16_f32 v35, v4, v1
	v_lshl_add_u64 v[4:5], v[2:3], 0, v[6:7]
	global_store_short v[4:5], v35, off
	v_mul_f32_e32 v4, v165, v177
	v_mul_f32_e32 v4, v4, v34
	v_cvt_pk_bf16_f32 v4, v4, v1
	global_store_short v[8:9], v4, off offset:448
	v_mul_f32_e32 v4, v137, v176
	v_mul_f32_e32 v4, v4, v34
	v_cvt_pk_bf16_f32 v4, v4, v1
	global_store_short v[10:11], v4, off offset:448
	v_mul_f32_e32 v4, v139, v175
	v_mul_f32_e32 v4, v4, v34
	v_cvt_pk_bf16_f32 v4, v4, v1
	global_store_short v[12:13], v4, off offset:448
	v_mul_f32_e32 v4, v138, v171
	v_mul_f32_e32 v4, v4, v34
	v_cvt_pk_bf16_f32 v4, v4, v1
	global_store_short v[14:15], v4, off offset:448
	v_mul_f32_e32 v4, v141, v172
	v_mul_f32_e32 v4, v4, v34
	v_cvt_pk_bf16_f32 v4, v4, v1
	global_store_short v[16:17], v4, off offset:448
	v_mul_f32_e32 v4, v140, v168
	v_mul_f32_e32 v4, v4, v34
	v_cvt_pk_bf16_f32 v6, v4, v1
	v_lshl_add_u64 v[4:5], v[2:3], 0, v[18:19]
	global_store_short v[4:5], v6, off
	v_mul_f32_e32 v4, v144, v166
	v_mul_f32_e32 v4, v4, v34
	v_cvt_pk_bf16_f32 v6, v4, v1
	v_lshl_add_u64 v[4:5], v[2:3], 0, v[20:21]
	global_store_short v[4:5], v6, off
	v_mul_f32_e32 v4, v142, v161
	v_mul_f32_e32 v4, v4, v34
	v_cvt_pk_bf16_f32 v6, v4, v1
	v_lshl_add_u64 v[4:5], v[2:3], 0, v[22:23]
	global_store_short v[4:5], v6, off
	v_mul_f32_e32 v4, v146, v154
	v_mul_f32_e32 v4, v4, v34
	v_cvt_pk_bf16_f32 v4, v4, v1
	global_store_short v[24:25], v4, off offset:448
	v_mul_f32_e32 v4, v143, v147
	v_mul_f32_e32 v4, v4, v34
	v_cvt_pk_bf16_f32 v4, v4, v1
	global_store_short v[26:27], v4, off offset:448
	v_mul_f32_e32 v4, v167, v149
	v_mul_f32_e32 v4, v4, v34
	v_cvt_pk_bf16_f32 v4, v4, v1
	global_store_short v[28:29], v4, off offset:448
	v_mul_f32_e32 v4, v145, v148
	v_mul_f32_e32 v4, v4, v34
	v_cvt_pk_bf16_f32 v4, v4, v1
	global_store_short v[30:31], v4, off offset:448
	v_mul_f32_e32 v4, v170, v158
	v_mul_f32_e32 v4, v4, v34
	v_cvt_pk_bf16_f32 v4, v4, v1
	global_store_short v[32:33], v4, off offset:448
	v_mul_f32_e32 v4, v169, v156
	v_mul_f32_e32 v4, v4, v34
	v_lshl_add_u64 v[2:3], v[2:3], 0, v[0:1]
	v_cvt_pk_bf16_f32 v4, v4, v1
	global_store_short v[2:3], v4, off
